# P5 ple-gate GEMM starts with the tile the workgroup finished last in P4 (tile order wg+256, wg), so its x / xg2 rows are the most recently written (cache residency); plus attention packed split
# baseline (speedup 1.0000x reference)
.LBB0_950:
	v_mov_b32_e32 v12, v196
	s_waitcnt lgkmcnt(0)
	s_barrier
	s_mov_b32 s50, 16
	v_readfirstlane_b32 s2, v12
	s_and_b64 vcc, exec, s[38:39]
	s_cbranch_vccnz .LBB0_1028
	v_lshlrev_b32_e32 v0, 4, v12
	v_add_u32_e32 v2, 0x2000, v0
	v_ashrrev_i32_e32 v3, 31, v2
	v_lshrrev_b32_e32 v3, 22, v3
	v_add_u32_e32 v3, v2, v3
	v_ashrrev_i32_e32 v6, 10, v3
	v_mul_i32_i24_e32 v3, 0x400, v6
	v_sub_u32_e32 v2, v2, v3
	v_lshrrev_b32_e32 v3, 4, v2
	v_bitop3_b32 v2, v3, v2, 32 bitop3:0x6c
	v_ashrrev_i32_e32 v3, 31, v2
	v_lshrrev_b32_e32 v3, 26, v3
	s_ashr_i32 s10, s2, 6
	v_add_u32_e32 v3, v2, v3
	v_lshlrev_b32_e32 v4, 3, v6
	s_ashr_i32 s3, s2, 8
	s_lshl_b32 s51, s10, 10
	s_lshl_b64 s[0:1], s[6:7], 1
	v_readlane_b32 s4, v253, 7
	v_ashrrev_i32_e32 v7, 6, v3
	v_and_b32_e32 v4, -16, v4
	s_add_u32 s52, s4, s0
	v_readlane_b32 s0, v253, 8
	v_add_u32_e32 v4, v7, v4
	s_addc_u32 s58, s0, s1
	v_and_b32_e32 v5, 3, v7
	s_mov_b32 s0, 0x1fffe0
	v_lshrrev_b32_e32 v8, 2, v4
	v_lshlrev_b32_e32 v9, 1, v4
	v_and_b32_e32 v3, 0xc0, v3
	v_and_or_b32 v5, v4, s0, v5
	v_and_b32_e32 v8, 4, v8
	v_and_b32_e32 v9, 24, v9
	v_sub_u32_e32 v2, v2, v3
	v_or3_b32 v5, v5, v8, v9
	v_lshlrev_b32_e32 v8, 5, v6
	v_ashrrev_i16_sdwa v2, v201, sext(v2) dst_sel:DWORD dst_unused:UNUSED_PAD src0_sel:DWORD src1_sel:BYTE_0
	v_and_b32_e32 v9, 32, v8
	v_bfe_i32 v8, v2, 0, 16
	v_add_lshl_u32 v2, v9, v8, 1
	v_lshl_add_u32 v162, v5, 11, v2
	v_lshl_add_u32 v164, v4, 11, v2
	v_bfe_i32 v2, v12, 27, 1
	v_lshrrev_b32_e32 v2, 22, v2
	v_add_u32_e32 v2, v0, v2
	v_and_b32_e32 v2, 0xfffffc00, v2
	v_sub_u32_e32 v0, v0, v2
	v_lshrrev_b32_e32 v2, 4, v0
	v_ashrrev_i32_e32 v3, 31, v12
	v_bitop3_b32 v0, v2, v0, 32 bitop3:0x6c
	v_lshrrev_b32_e32 v3, 26, v3
	v_ashrrev_i32_e32 v2, 31, v0
	v_add_u32_e32 v3, v12, v3
	v_lshrrev_b32_e32 v2, 26, v2
	v_ashrrev_i32_e32 v10, 6, v3
	v_add_u32_e32 v2, v0, v2
	v_lshlrev_b32_e32 v3, 3, v10
	v_ashrrev_i32_e32 v9, 6, v2
	v_and_b32_e32 v3, -16, v3
	v_add_u32_e32 v3, v9, v3
	v_and_b32_e32 v4, 3, v9
	v_lshrrev_b32_e32 v5, 2, v3
	v_lshlrev_b32_e32 v11, 1, v3
	v_and_b32_e32 v2, 0xc0, v2
	v_and_or_b32 v4, v3, s0, v4
	v_and_b32_e32 v5, 4, v5
	v_and_b32_e32 v11, 24, v11
	v_sub_u32_e32 v0, v0, v2
	v_or3_b32 v4, v4, v5, v11
	v_lshlrev_b32_e32 v5, 5, v10
	v_ashrrev_i16_sdwa v0, v201, sext(v0) dst_sel:DWORD dst_unused:UNUSED_PAD src0_sel:DWORD src1_sel:BYTE_0
	v_readlane_b32 s0, v253, 41
	v_and_b32_e32 v5, 32, v5
	v_bfe_i32 v11, v0, 0, 16
	v_readlane_b32 s1, v253, 42
	s_add_u32 s46, s52, s0
	v_add_lshl_u32 v2, v5, v11, 1
	s_addc_u32 s47, s58, s1
	s_add_i32 s59, s51, 0
	v_lshl_add_u32 v0, v4, 11, v2
	s_add_i32 m0, s59, 0x10000
	v_lshl_add_u32 v166, v3, 11, v2
	global_load_lds_dwordx4 v0, s[46:47]
	s_add_i32 m0, s59, 0x12000
	s_add_u32 s0, s46, 0x40000
	global_load_lds_dwordx4 v162, s[46:47]
	s_addc_u32 s1, s47, 0
	v_readlane_b32 s88, v253, 49
	v_readlane_b32 s89, v253, 50
	s_add_u32 s88, s88, 0x400000
	s_addc_u32 s89, s89, 0
	s_add_u32 s90, s88, 0x40000
	s_addc_u32 s91, s89, 0
	s_add_i32 m0, s59, 0x14000
	s_add_i32 s60, s59, 0x2000
	global_load_lds_dwordx4 v0, s[0:1]
	s_add_i32 m0, s59, 0x16000
	s_add_i32 s61, s59, 0x4000
	global_load_lds_dwordx4 v162, s[0:1]
	s_mov_b32 s0, s88
	s_mov_b32 m0, s59
	s_mov_b32 s1, s89
	s_add_i32 s62, s59, 0x6000
	v_mov_b32_e32 v163, v1
	s_cmp_eq_u32 s3, 1
	v_lshl_add_u64 v[2:3], s[46:47], 0, v[0:1]
	v_lshl_add_u64 v[4:5], s[46:47], 0, v[162:163]
	global_load_lds_dwordx4 v166, s[0:1]
	s_mov_b32 m0, s60
	s_nop 0
	global_load_lds_dwordx4 v164, s[0:1]
	s_mov_b32 s0, s90
	s_mov_b32 m0, s61
	s_mov_b32 s1, s91
	s_nop 4
	global_load_lds_dwordx4 v166, s[0:1]
	s_mov_b32 m0, s62
	s_nop 0
	global_load_lds_dwordx4 v164, s[0:1]
	s_cselect_b64 s[0:1], -1, 0
	s_cmp_lg_u32 s3, 1
	s_cbranch_scc1 .LBB0_953
	s_barrier
.LBB0_953:
	v_readlane_b32 s76, v251, 31
	v_and_b32_e32 v13, 15, v12
	v_bfe_u32 v18, v12, 4, 2
	s_lshl_b64 s[4:5], s[8:9], 2
	v_readlane_b32 s80, v251, 35
	v_lshl_or_b32 v212, s3, 6, v13
	v_lshlrev_b32_e32 v20, 4, v18
	s_mov_b32 s40, s88
	v_readlane_b32 s81, v251, 36
	s_add_u32 s4, s80, s4
	v_lshl_or_b32 v13, v13, 6, v20
	v_lshlrev_b32_e32 v20, 2, v212
	v_mov_b32_e32 v167, v1
	s_mov_b32 s41, s89
	s_addc_u32 s5, s81, s5
	s_and_b32 s63, s10, 3
	s_lshl_b32 s3, s3, 13
	v_and_b32_e32 v21, 32, v20
	s_add_i32 m0, s59, 0x18000
	v_lshl_add_u64 v[2:3], v[2:3], 0, s[54:55]
	v_lshl_add_u64 v[14:15], s[40:41], 0, v[166:167]
	v_mov_b32_e32 v165, v1
	v_bitop3_b32 v21, v13, s3, v21 bitop3:0xde
	s_lshl_b32 s3, s63, 12
	s_waitcnt vmcnt(2)
	s_barrier
	global_load_lds_dwordx4 v[2:3], off
	v_lshl_add_u64 v[2:3], v[4:5], 0, s[54:55]
	s_add_i32 m0, s59, 0x1a000
	s_add_i32 s64, s59, 0x8000
	s_add_i32 s65, s59, 0xa000
	v_lshl_add_u64 v[16:17], s[40:41], 0, v[164:165]
	global_load_lds_dwordx4 v[2:3], off
	v_lshl_add_u64 v[2:3], v[14:15], 0, s[54:55]
	s_mov_b32 m0, s64
	s_add_u32 s6, s46, 0x40080
	global_load_lds_dwordx4 v[2:3], off
	v_lshl_add_u64 v[2:3], v[16:17], 0, s[54:55]
	s_mov_b32 m0, s65
	s_addc_u32 s7, s47, 0
	global_load_lds_dwordx4 v[2:3], off
	s_add_i32 m0, s59, 0x1c000
	v_lshl_add_u64 v[2:3], s[6:7], 0, v[0:1]
	global_load_lds_dwordx4 v[2:3], off
	v_lshl_add_u64 v[2:3], s[6:7], 0, v[162:163]
	s_add_i32 m0, s59, 0x1e000
	s_cmp_gt_i32 s50, 0
	global_load_lds_dwordx4 v[2:3], off
	v_lshlrev_b32_e32 v2, 14, v10
	v_and_b32_e32 v2, 0xffff8000, v2
	v_lshl_add_u32 v2, v9, 11, v2
	v_and_b32_e32 v3, 1, v10
	v_lshl_or_b32 v2, v3, 6, v2
	v_lshlrev_b32_e32 v12, 2, v12
	s_cselect_b64 s[6:7], -1, 0
	s_add_i32 s67, s50, -2
	v_lshl_add_u32 v168, v11, 1, v2
	v_lshlrev_b32_e32 v2, 14, v6
	v_and_b32_e32 v12, 32, v12
	s_cmpk_lt_u32 s2, 0x100
	v_readlane_b32 s2, v254, 30
	v_and_b32_e32 v2, 0xffff8000, v2
	v_bitop3_b32 v213, v13, s3, v12 bitop3:0xde
	s_waitcnt vmcnt(6)
	v_add_u32_e32 v215, s2, v20
	v_lshl_add_u32 v2, v7, 11, v2
	v_and_b32_e32 v3, 1, v6
	v_readlane_b32 s2, v253, 43
	v_readlane_b32 s77, v251, 32
	v_lshlrev_b32_e32 v19, 3, v18
	v_lshl_or_b32 v2, v3, 6, v2
	v_readlane_b32 s3, v253, 44
	s_mov_b32 s66, 0
	v_lshl_or_b32 v214, s63, 5, v19
	s_cselect_b64 s[8:9], -1, 0
	v_cmp_eq_u32_e64 s[38:39], 0, v18
	v_mov_b32_e32 v169, v1
	v_lshl_add_u32 v170, v8, 1, v2
	v_mov_b32_e32 v171, v1
	v_add_u32_e32 v216, 0, v21
	v_readlane_b32 s76, v253, 31
	s_add_i32 s77, s2, 8
	s_mov_b64 s[2:3], s[40:41]
	v_readlane_b32 s78, v251, 33
	v_readlane_b32 s79, v251, 34
	v_readlane_b32 s82, v251, 37
	v_readlane_b32 s83, v251, 38
	v_readlane_b32 s84, v251, 39
	v_readlane_b32 s85, v251, 40
	v_readlane_b32 s86, v251, 41
	v_readlane_b32 s87, v251, 42
	v_readlane_b32 s88, v251, 43
	v_readlane_b32 s89, v251, 44
	v_readlane_b32 s90, v251, 45
	v_readlane_b32 s91, v251, 46
	s_barrier
	s_branch .LBB0_956

.LBB0_956:
	s_add_i32 s66, s66, 1
	s_mul_i32 s11, s66, s33
	s_mul_hi_u32 s13, s66, s71
	s_add_i32 s13, s13, s11
	s_mul_i32 s11, s66, s71
	s_add_u32 s42, s11, s22
	s_addc_u32 s43, s13, s23
	v_cmp_gt_i64_e32 vcc, s[42:43], v[160:161]
	v_cmp_lt_i64_e64 s[40:41], s[42:43], v[158:159]
	s_xor_b32 s42, s42, 0x100
	s_cbranch_vccnz .LBB0_962
	s_ashr_i32 s10, s42, 31
	s_lshr_b32 s10, s10, 29
	s_add_i32 s12, s42, s10
	s_and_b32 s10, s12, -8
	s_sub_i32 s13, s42, s10
	s_cmp_gt_i32 s13, -1
	s_mov_b64 s[10:11], -1
	s_cbranch_scc0 .LBB0_959
	s_lshl_b32 s42, s13, 6
	s_mov_b64 s[10:11], 0
